# keys (kz) kept in MFMA-fragment order by the in-proj epilogue; intra-chunk phase and retention scan read that order, the scan feeds K.V MFMA directly from its coalesced loads (no LDS staging / fragmen
# speedup vs baseline: 1.1639x; 1.0154x over previous
.LBB0_1082:
	v_lshlrev_b32_e32 v0, 3, v185
	v_cndmask_b32_e64 v83, 0, 1, s[2:3]
	v_and_b32_e32 v0, 56, v0
	v_cmp_ne_u32_e64 s[4:5], 1, v83
	v_ashrrev_i32_e32 v163, 3, v185
	v_and_b32_e32 v83, 0xffffff80, v185
	v_add_u32_e32 v86, 64, v185
	v_add_u32_e32 v87, 0x80, v185
	v_add_u32_e32 v134, 0xc0, v185
	v_and_b32_e32 v164, 0xffffff00, v115
	v_ashrrev_i32_e32 v115, 31, v114
	v_lshl_add_u32 v82, v0, 1, v202
	s_andn2_b64 vcc, exec, s[2:3]
	v_lshlrev_b32_e32 v0, 1, v0
	v_and_or_b32 v83, v163, 15, v83
	v_ashrrev_i32_e32 v161, 3, v86
	v_and_b32_e32 v162, 0xffffff80, v86
	v_ashrrev_i32_e32 v157, 3, v87
	v_and_b32_e32 v160, 0xffffff80, v87
	v_ashrrev_i32_e32 v149, 3, v134
	v_and_b32_e32 v156, 0xffffff80, v134
	v_add_u32_e32 v148, 0x800, v186
	s_cbranch_vccnz .LBB0_1084
	v_or_b32_e32 v86, v187, v164
	v_mul_i32_i24_e32 v86, 0x4200, v86
	v_readlane_b32 s2, v252, 31
	v_ashrrev_i32_e32 v87, 31, v86
	v_readlane_b32 s3, v252, 32
	s_nop 1
	v_lshl_add_u64 v[86:87], s[2:3], 0, v[86:87]
	v_mad_u64_u32 v[138:139], s[2:3], v163, s25, v[82:83]
	ds_read_b128 v[134:137], v138
	v_lshl_add_u64 v[86:87], v[114:115], 1, v[86:87]
	v_lshl_add_u64 v[86:87], v[86:87], 0, v[0:1]
	v_mad_i64_i32 v[140:141], s[2:3], v83, s88, v[86:87]
	s_waitcnt lgkmcnt(0)
	v_or_b32_e32 v244, v187, v164
	v_lshrrev_b32_e32 v245, 3, v185
	v_add_u32_e32 v244, v244, v245
	v_and_b32_e32 v245, 7, v185
	v_lshl_add_u32 v245, v245, 3, v114
	v_lshrrev_b32_e32 v246, 5, v244
	v_mul_u32_u24_e32 v246, 0x42, v246
	v_lshrrev_b32_e32 v247, 7, v245
	v_add_u32_e32 v246, v246, v247
	v_lshlrev_b32_e32 v246, 13, v246
	v_bfe_u32 v247, v244, 4, 1
	v_lshlrev_b32_e32 v247, 2, v247
	v_bfe_u32 v248, v245, 5, 2
	v_add_u32_e32 v247, v247, v248
	v_lshl_add_u32 v246, v247, 10, v246
	v_bfe_u32 v247, v245, 3, 2
	v_lshlrev_b32_e32 v247, 4, v247
	v_and_b32_e32 v248, 15, v244
	v_add_u32_e32 v247, v247, v248
	v_lshl_add_u32 v246, v247, 4, v246
	v_mov_b32_e32 v247, 0
	v_readlane_b32 s98, v252, 31
	v_readlane_b32 s99, v252, 32
	s_nop 1
	v_lshl_add_u64 v[246:247], s[98:99], 0, v[246:247]
	global_store_dwordx4 v[246:247], v[134:137], off
	v_mad_u64_u32 v[140:141], s[2:3], v161, s25, v[82:83]
	ds_read_b128 v[134:137], v140
	v_and_or_b32 v139, v161, 15, v162
	v_mad_i64_i32 v[142:143], s[2:3], v139, s88, v[86:87]
	v_and_or_b32 v141, v157, 15, v160
	s_waitcnt lgkmcnt(0)
	v_or_b32_e32 v244, v187, v164
	v_lshrrev_b32_e32 v245, 3, v185
	v_add_u32_e32 v244, v244, v245
	v_add_u32_e32 v244, 0x8, v244
	v_and_b32_e32 v245, 7, v185
	v_lshl_add_u32 v245, v245, 3, v114
	v_lshrrev_b32_e32 v246, 5, v244
	v_mul_u32_u24_e32 v246, 0x42, v246
	v_lshrrev_b32_e32 v247, 7, v245
	v_add_u32_e32 v246, v246, v247
	v_lshlrev_b32_e32 v246, 13, v246
	v_bfe_u32 v247, v244, 4, 1
	v_lshlrev_b32_e32 v247, 2, v247
	v_bfe_u32 v248, v245, 5, 2
	v_add_u32_e32 v247, v247, v248
	v_lshl_add_u32 v246, v247, 10, v246
	v_bfe_u32 v247, v245, 3, 2
	v_lshlrev_b32_e32 v247, 4, v247
	v_and_b32_e32 v248, 15, v244
	v_add_u32_e32 v247, v247, v248
	v_lshl_add_u32 v246, v247, 4, v246
	v_mov_b32_e32 v247, 0
	v_readlane_b32 s98, v252, 31
	v_readlane_b32 s99, v252, 32
	s_nop 1
	v_lshl_add_u64 v[246:247], s[98:99], 0, v[246:247]
	global_store_dwordx4 v[246:247], v[134:137], off
	v_mad_u64_u32 v[142:143], s[2:3], v157, s25, v[82:83]
	ds_read_b128 v[134:137], v142
	v_mad_i64_i32 v[176:177], s[2:3], v141, s88, v[86:87]
	v_and_or_b32 v143, v149, 15, v156
	v_mad_i64_i32 v[178:179], s[2:3], v143, s88, v[86:87]
	s_waitcnt lgkmcnt(0)
	v_or_b32_e32 v244, v187, v164
	v_lshrrev_b32_e32 v245, 3, v185
	v_add_u32_e32 v244, v244, v245
	v_add_u32_e32 v244, 0x80, v244
	v_and_b32_e32 v245, 7, v185
	v_lshl_add_u32 v245, v245, 3, v114
	v_lshrrev_b32_e32 v246, 5, v244
	v_mul_u32_u24_e32 v246, 0x42, v246
	v_lshrrev_b32_e32 v247, 7, v245
	v_add_u32_e32 v246, v246, v247
	v_lshlrev_b32_e32 v246, 13, v246
	v_bfe_u32 v247, v244, 4, 1
	v_lshlrev_b32_e32 v247, 2, v247
	v_bfe_u32 v248, v245, 5, 2
	v_add_u32_e32 v247, v247, v248
	v_lshl_add_u32 v246, v247, 10, v246
	v_bfe_u32 v247, v245, 3, 2
	v_lshlrev_b32_e32 v247, 4, v247
	v_and_b32_e32 v248, 15, v244
	v_add_u32_e32 v247, v247, v248
	v_lshl_add_u32 v246, v247, 4, v246
	v_mov_b32_e32 v247, 0
	v_readlane_b32 s98, v252, 31
	v_readlane_b32 s99, v252, 32
	s_nop 1
	v_lshl_add_u64 v[246:247], s[98:99], 0, v[246:247]
	global_store_dwordx4 v[246:247], v[134:137], off
	v_mad_u64_u32 v[176:177], s[2:3], v149, s25, v[82:83]
	ds_read_b128 v[134:137], v176
	s_mov_b64 s[2:3], 0x1080000
	s_waitcnt lgkmcnt(0)
	v_or_b32_e32 v244, v187, v164
	v_lshrrev_b32_e32 v245, 3, v185
	v_add_u32_e32 v244, v244, v245
	v_add_u32_e32 v244, 0x88, v244
	v_and_b32_e32 v245, 7, v185
	v_lshl_add_u32 v245, v245, 3, v114
	v_lshrrev_b32_e32 v246, 5, v244
	v_mul_u32_u24_e32 v246, 0x42, v246
	v_lshrrev_b32_e32 v247, 7, v245
	v_add_u32_e32 v246, v246, v247
	v_lshlrev_b32_e32 v246, 13, v246
	v_bfe_u32 v247, v244, 4, 1
	v_lshlrev_b32_e32 v247, 2, v247
	v_bfe_u32 v248, v245, 5, 2
	v_add_u32_e32 v247, v247, v248
	v_lshl_add_u32 v246, v247, 10, v246
	v_bfe_u32 v247, v245, 3, 2
	v_lshlrev_b32_e32 v247, 4, v247
	v_and_b32_e32 v248, 15, v244
	v_add_u32_e32 v247, v247, v248
	v_lshl_add_u32 v246, v247, 4, v246
	v_mov_b32_e32 v247, 0
	v_readlane_b32 s98, v252, 31
	v_readlane_b32 s99, v252, 32
	s_nop 1
	v_lshl_add_u64 v[246:247], s[98:99], 0, v[246:247]
	global_store_dwordx4 v[246:247], v[134:137], off
	ds_write2_b64 v186, v[144:145], v[152:153] offset1:4
	ds_write2_b64 v148, v[146:147], v[154:155] offset0:32 offset1:36
	ds_write2_b64 v186, v[150:151], v[84:85] offset0:8 offset1:12
	ds_write2_b64 v148, v[158:159], v[88:89] offset0:40 offset1:44
	v_lshl_add_u64 v[88:89], v[86:87], 0, s[2:3]
	ds_read_b128 v[84:87], v138
	v_mad_i64_i32 v[134:135], s[2:3], v83, s88, v[88:89]
	s_waitcnt lgkmcnt(0)
	v_or_b32_e32 v244, v187, v164
	v_lshrrev_b32_e32 v245, 3, v185
	v_add_u32_e32 v244, v244, v245
	v_and_b32_e32 v245, 7, v185
	v_lshl_add_u32 v245, v245, 3, v114
	v_lshrrev_b32_e32 v246, 5, v244
	v_mul_u32_u24_e32 v246, 0x42, v246
	v_lshrrev_b32_e32 v247, 7, v245
	v_add_u32_e32 v246, v246, v247
	v_lshlrev_b32_e32 v246, 13, v246
	v_bfe_u32 v247, v244, 4, 1
	v_lshlrev_b32_e32 v247, 2, v247
	v_bfe_u32 v248, v245, 5, 2
	v_add_u32_e32 v247, v247, v248
	v_lshl_add_u32 v246, v247, 10, v246
	v_bfe_u32 v247, v245, 3, 2
	v_lshlrev_b32_e32 v247, 4, v247
	v_and_b32_e32 v248, 15, v244
	v_add_u32_e32 v247, v247, v248
	v_lshl_add_u32 v246, v247, 4, v246
	v_add_u32_e32 v246, 0x1080000, v246
	v_mov_b32_e32 v247, 0
	v_readlane_b32 s98, v252, 31
	v_readlane_b32 s99, v252, 32
	s_nop 1
	v_lshl_add_u64 v[246:247], s[98:99], 0, v[246:247]
	global_store_dwordx4 v[246:247], v[84:87], off
	ds_read_b128 v[84:87], v140
	v_mad_i64_i32 v[134:135], s[2:3], v139, s88, v[88:89]
	s_waitcnt lgkmcnt(0)
	v_or_b32_e32 v244, v187, v164
	v_lshrrev_b32_e32 v245, 3, v185
	v_add_u32_e32 v244, v244, v245
	v_add_u32_e32 v244, 0x8, v244
	v_and_b32_e32 v245, 7, v185
	v_lshl_add_u32 v245, v245, 3, v114
	v_lshrrev_b32_e32 v246, 5, v244
	v_mul_u32_u24_e32 v246, 0x42, v246
	v_lshrrev_b32_e32 v247, 7, v245
	v_add_u32_e32 v246, v246, v247
	v_lshlrev_b32_e32 v246, 13, v246
	v_bfe_u32 v247, v244, 4, 1
	v_lshlrev_b32_e32 v247, 2, v247
	v_bfe_u32 v248, v245, 5, 2
	v_add_u32_e32 v247, v247, v248
	v_lshl_add_u32 v246, v247, 10, v246
	v_bfe_u32 v247, v245, 3, 2
	v_lshlrev_b32_e32 v247, 4, v247
	v_and_b32_e32 v248, 15, v244
	v_add_u32_e32 v247, v247, v248
	v_lshl_add_u32 v246, v247, 4, v246
	v_add_u32_e32 v246, 0x1080000, v246
	v_mov_b32_e32 v247, 0
	v_readlane_b32 s98, v252, 31
	v_readlane_b32 s99, v252, 32
	s_nop 1
	v_lshl_add_u64 v[246:247], s[98:99], 0, v[246:247]
	global_store_dwordx4 v[246:247], v[84:87], off
	ds_read_b128 v[84:87], v142
	v_mad_i64_i32 v[134:135], s[2:3], v141, s88, v[88:89]
	v_mad_i64_i32 v[88:89], s[2:3], v143, s88, v[88:89]
	s_waitcnt lgkmcnt(0)
	v_or_b32_e32 v244, v187, v164
	v_lshrrev_b32_e32 v245, 3, v185
	v_add_u32_e32 v244, v244, v245
	v_add_u32_e32 v244, 0x80, v244
	v_and_b32_e32 v245, 7, v185
	v_lshl_add_u32 v245, v245, 3, v114
	v_lshrrev_b32_e32 v246, 5, v244
	v_mul_u32_u24_e32 v246, 0x42, v246
	v_lshrrev_b32_e32 v247, 7, v245
	v_add_u32_e32 v246, v246, v247
	v_lshlrev_b32_e32 v246, 13, v246
	v_bfe_u32 v247, v244, 4, 1
	v_lshlrev_b32_e32 v247, 2, v247
	v_bfe_u32 v248, v245, 5, 2
	v_add_u32_e32 v247, v247, v248
	v_lshl_add_u32 v246, v247, 10, v246
	v_bfe_u32 v247, v245, 3, 2
	v_lshlrev_b32_e32 v247, 4, v247
	v_and_b32_e32 v248, 15, v244
	v_add_u32_e32 v247, v247, v248
	v_lshl_add_u32 v246, v247, 4, v246
	v_add_u32_e32 v246, 0x1080000, v246
	v_mov_b32_e32 v247, 0
	v_readlane_b32 s98, v252, 31
	v_readlane_b32 s99, v252, 32
	s_nop 1
	v_lshl_add_u64 v[246:247], s[98:99], 0, v[246:247]
	global_store_dwordx4 v[246:247], v[84:87], off
	ds_read_b128 v[84:87], v176
	s_waitcnt lgkmcnt(0)
	v_or_b32_e32 v244, v187, v164
	v_lshrrev_b32_e32 v245, 3, v185
	v_add_u32_e32 v244, v244, v245
	v_add_u32_e32 v244, 0x88, v244
	v_and_b32_e32 v245, 7, v185
	v_lshl_add_u32 v245, v245, 3, v114
	v_lshrrev_b32_e32 v246, 5, v244
	v_mul_u32_u24_e32 v246, 0x42, v246
	v_lshrrev_b32_e32 v247, 7, v245
	v_add_u32_e32 v246, v246, v247
	v_lshlrev_b32_e32 v246, 13, v246
	v_bfe_u32 v247, v244, 4, 1
	v_lshlrev_b32_e32 v247, 2, v247
	v_bfe_u32 v248, v245, 5, 2
	v_add_u32_e32 v247, v247, v248
	v_lshl_add_u32 v246, v247, 10, v246
	v_bfe_u32 v247, v245, 3, 2
	v_lshlrev_b32_e32 v247, 4, v247
	v_and_b32_e32 v248, 15, v244
	v_add_u32_e32 v247, v247, v248
	v_lshl_add_u32 v246, v247, 4, v246
	v_add_u32_e32 v246, 0x1080000, v246
	v_mov_b32_e32 v247, 0
	v_readlane_b32 s98, v252, 31
	v_readlane_b32 s99, v252, 32
	s_nop 1
	v_lshl_add_u64 v[246:247], s[98:99], 0, v[246:247]
	global_store_dwordx4 v[246:247], v[84:87], off

.LBB0_1101:
	v_or_b32_e32 v50, v146, v164
	v_mul_i32_i24_e32 v50, 0x4200, v50
	v_readlane_b32 s0, v252, 31
	v_ashrrev_i32_e32 v51, 31, v50
	v_readlane_b32 s1, v252, 32
	s_nop 1
	v_lshl_add_u64 v[50:51], s[0:1], 0, v[50:51]
	v_lshl_add_u64 v[50:51], v[114:115], 1, v[50:51]
	v_mad_u64_u32 v[64:65], s[0:1], v163, s25, v[82:83]
	v_lshl_add_u64 v[62:63], v[50:51], 0, v[0:1]
	ds_read_b128 v[50:53], v64
	v_mad_i64_i32 v[70:71], s[0:1], v83, s88, v[62:63]
	v_and_or_b32 v0, v161, 15, v162
	v_mad_i64_i32 v[72:73], s[0:1], v0, s88, v[62:63]
	s_waitcnt lgkmcnt(0)
	v_or_b32_e32 v244, v146, v164
	v_lshrrev_b32_e32 v245, 3, v185
	v_add_u32_e32 v244, v244, v245
	v_and_b32_e32 v245, 7, v185
	v_lshl_add_u32 v245, v245, 3, v114
	v_lshrrev_b32_e32 v246, 5, v244
	v_mul_u32_u24_e32 v246, 0x42, v246
	v_lshrrev_b32_e32 v247, 7, v245
	v_add_u32_e32 v246, v246, v247
	v_lshlrev_b32_e32 v246, 13, v246
	v_bfe_u32 v247, v244, 4, 1
	v_lshlrev_b32_e32 v247, 2, v247
	v_bfe_u32 v248, v245, 5, 2
	v_add_u32_e32 v247, v247, v248
	v_lshl_add_u32 v246, v247, 10, v246
	v_bfe_u32 v247, v245, 3, 2
	v_lshlrev_b32_e32 v247, 4, v247
	v_and_b32_e32 v248, 15, v244
	v_add_u32_e32 v247, v247, v248
	v_lshl_add_u32 v246, v247, 4, v246
	v_mov_b32_e32 v247, 0
	v_readlane_b32 s98, v252, 31
	v_readlane_b32 s99, v252, 32
	s_nop 1
	v_lshl_add_u64 v[246:247], s[98:99], 0, v[246:247]
	global_store_dwordx4 v[246:247], v[50:53], off
	v_mad_u64_u32 v[70:71], s[0:1], v161, s25, v[82:83]
	ds_read_b128 v[50:53], v70
	v_and_or_b32 v65, v157, 15, v160
	v_mad_i64_i32 v[78:79], s[0:1], v65, s88, v[62:63]
	v_and_or_b32 v71, v149, 15, v156
	s_waitcnt lgkmcnt(0)
	v_or_b32_e32 v244, v146, v164
	v_lshrrev_b32_e32 v245, 3, v185
	v_add_u32_e32 v244, v244, v245
	v_add_u32_e32 v244, 0x8, v244
	v_and_b32_e32 v245, 7, v185
	v_lshl_add_u32 v245, v245, 3, v114
	v_lshrrev_b32_e32 v246, 5, v244
	v_mul_u32_u24_e32 v246, 0x42, v246
	v_lshrrev_b32_e32 v247, 7, v245
	v_add_u32_e32 v246, v246, v247
	v_lshlrev_b32_e32 v246, 13, v246
	v_bfe_u32 v247, v244, 4, 1
	v_lshlrev_b32_e32 v247, 2, v247
	v_bfe_u32 v248, v245, 5, 2
	v_add_u32_e32 v247, v247, v248
	v_lshl_add_u32 v246, v247, 10, v246
	v_bfe_u32 v247, v245, 3, 2
	v_lshlrev_b32_e32 v247, 4, v247
	v_and_b32_e32 v248, 15, v244
	v_add_u32_e32 v247, v247, v248
	v_lshl_add_u32 v246, v247, 4, v246
	v_mov_b32_e32 v247, 0
	v_readlane_b32 s98, v252, 31
	v_readlane_b32 s99, v252, 32
	s_nop 1
	v_lshl_add_u64 v[246:247], s[98:99], 0, v[246:247]
	global_store_dwordx4 v[246:247], v[50:53], off
	v_mad_u64_u32 v[72:73], s[0:1], v157, s25, v[82:83]
	ds_read_b128 v[50:53], v72
	v_mad_i64_i32 v[80:81], s[0:1], v71, s88, v[62:63]
	s_waitcnt lgkmcnt(0)
	v_or_b32_e32 v244, v146, v164
	v_lshrrev_b32_e32 v245, 3, v185
	v_add_u32_e32 v244, v244, v245
	v_add_u32_e32 v244, 0x80, v244
	v_and_b32_e32 v245, 7, v185
	v_lshl_add_u32 v245, v245, 3, v114
	v_lshrrev_b32_e32 v246, 5, v244
	v_mul_u32_u24_e32 v246, 0x42, v246
	v_lshrrev_b32_e32 v247, 7, v245
	v_add_u32_e32 v246, v246, v247
	v_lshlrev_b32_e32 v246, 13, v246
	v_bfe_u32 v247, v244, 4, 1
	v_lshlrev_b32_e32 v247, 2, v247
	v_bfe_u32 v248, v245, 5, 2
	v_add_u32_e32 v247, v247, v248
	v_lshl_add_u32 v246, v247, 10, v246
	v_bfe_u32 v247, v245, 3, 2
	v_lshlrev_b32_e32 v247, 4, v247
	v_and_b32_e32 v248, 15, v244
	v_add_u32_e32 v247, v247, v248
	v_lshl_add_u32 v246, v247, 4, v246
	v_mov_b32_e32 v247, 0
	v_readlane_b32 s98, v252, 31
	v_readlane_b32 s99, v252, 32
	s_nop 1
	v_lshl_add_u64 v[246:247], s[98:99], 0, v[246:247]
	global_store_dwordx4 v[246:247], v[50:53], off
	v_mad_u64_u32 v[78:79], s[0:1], v149, s25, v[82:83]
	ds_read_b128 v[50:53], v78
	s_mov_b64 s[0:1], 0x1080000
	s_waitcnt lgkmcnt(0)
	v_or_b32_e32 v244, v146, v164
	v_lshrrev_b32_e32 v245, 3, v185
	v_add_u32_e32 v244, v244, v245
	v_add_u32_e32 v244, 0x88, v244
	v_and_b32_e32 v245, 7, v185
	v_lshl_add_u32 v245, v245, 3, v114
	v_lshrrev_b32_e32 v246, 5, v244
	v_mul_u32_u24_e32 v246, 0x42, v246
	v_lshrrev_b32_e32 v247, 7, v245
	v_add_u32_e32 v246, v246, v247
	v_lshlrev_b32_e32 v246, 13, v246
	v_bfe_u32 v247, v244, 4, 1
	v_lshlrev_b32_e32 v247, 2, v247
	v_bfe_u32 v248, v245, 5, 2
	v_add_u32_e32 v247, v247, v248
	v_lshl_add_u32 v246, v247, 10, v246
	v_bfe_u32 v247, v245, 3, 2
	v_lshlrev_b32_e32 v247, 4, v247
	v_and_b32_e32 v248, 15, v244
	v_add_u32_e32 v247, v247, v248
	v_lshl_add_u32 v246, v247, 4, v246
	v_mov_b32_e32 v247, 0
	v_readlane_b32 s98, v252, 31
	v_readlane_b32 s99, v252, 32
	s_nop 1
	v_lshl_add_u64 v[246:247], s[98:99], 0, v[246:247]
	global_store_dwordx4 v[246:247], v[50:53], off
	ds_write2_b64 v186, v[74:75], v[66:67] offset1:4
	ds_write2_b64 v148, v[76:77], v[68:69] offset0:32 offset1:36
	ds_write2_b64 v186, v[58:59], v[54:55] offset0:8 offset1:12
	ds_write2_b64 v148, v[60:61], v[56:57] offset0:40 offset1:44
	ds_read_b128 v[50:53], v64
	v_lshl_add_u64 v[54:55], v[62:63], 0, s[0:1]
	v_mad_i64_i32 v[56:57], s[0:1], v83, s88, v[54:55]
	s_waitcnt lgkmcnt(0)
	v_or_b32_e32 v244, v146, v164
	v_lshrrev_b32_e32 v245, 3, v185
	v_add_u32_e32 v244, v244, v245
	v_and_b32_e32 v245, 7, v185
	v_lshl_add_u32 v245, v245, 3, v114
	v_lshrrev_b32_e32 v246, 5, v244
	v_mul_u32_u24_e32 v246, 0x42, v246
	v_lshrrev_b32_e32 v247, 7, v245
	v_add_u32_e32 v246, v246, v247
	v_lshlrev_b32_e32 v246, 13, v246
	v_bfe_u32 v247, v244, 4, 1
	v_lshlrev_b32_e32 v247, 2, v247
	v_bfe_u32 v248, v245, 5, 2
	v_add_u32_e32 v247, v247, v248
	v_lshl_add_u32 v246, v247, 10, v246
	v_bfe_u32 v247, v245, 3, 2
	v_lshlrev_b32_e32 v247, 4, v247
	v_and_b32_e32 v248, 15, v244
	v_add_u32_e32 v247, v247, v248
	v_lshl_add_u32 v246, v247, 4, v246
	v_add_u32_e32 v246, 0x1080000, v246
	v_mov_b32_e32 v247, 0
	v_readlane_b32 s98, v252, 31
	v_readlane_b32 s99, v252, 32
	s_nop 1
	v_lshl_add_u64 v[246:247], s[98:99], 0, v[246:247]
	global_store_dwordx4 v[246:247], v[50:53], off
	ds_read_b128 v[50:53], v70
	v_mad_i64_i32 v[56:57], s[0:1], v0, s88, v[54:55]
	s_waitcnt lgkmcnt(0)
	v_or_b32_e32 v244, v146, v164
	v_lshrrev_b32_e32 v245, 3, v185
	v_add_u32_e32 v244, v244, v245
	v_add_u32_e32 v244, 0x8, v244
	v_and_b32_e32 v245, 7, v185
	v_lshl_add_u32 v245, v245, 3, v114
	v_lshrrev_b32_e32 v246, 5, v244
	v_mul_u32_u24_e32 v246, 0x42, v246
	v_lshrrev_b32_e32 v247, 7, v245
	v_add_u32_e32 v246, v246, v247
	v_lshlrev_b32_e32 v246, 13, v246
	v_bfe_u32 v247, v244, 4, 1
	v_lshlrev_b32_e32 v247, 2, v247
	v_bfe_u32 v248, v245, 5, 2
	v_add_u32_e32 v247, v247, v248
	v_lshl_add_u32 v246, v247, 10, v246
	v_bfe_u32 v247, v245, 3, 2
	v_lshlrev_b32_e32 v247, 4, v247
	v_and_b32_e32 v248, 15, v244
	v_add_u32_e32 v247, v247, v248
	v_lshl_add_u32 v246, v247, 4, v246
	v_add_u32_e32 v246, 0x1080000, v246
	v_mov_b32_e32 v247, 0
	v_readlane_b32 s98, v252, 31
	v_readlane_b32 s99, v252, 32
	s_nop 1
	v_lshl_add_u64 v[246:247], s[98:99], 0, v[246:247]
	global_store_dwordx4 v[246:247], v[50:53], off
	ds_read_b128 v[50:53], v72
	v_mad_i64_i32 v[56:57], s[0:1], v65, s88, v[54:55]
	v_mad_i64_i32 v[54:55], s[0:1], v71, s88, v[54:55]
	s_waitcnt lgkmcnt(0)
	v_or_b32_e32 v244, v146, v164
	v_lshrrev_b32_e32 v245, 3, v185
	v_add_u32_e32 v244, v244, v245
	v_add_u32_e32 v244, 0x80, v244
	v_and_b32_e32 v245, 7, v185
	v_lshl_add_u32 v245, v245, 3, v114
	v_lshrrev_b32_e32 v246, 5, v244
	v_mul_u32_u24_e32 v246, 0x42, v246
	v_lshrrev_b32_e32 v247, 7, v245
	v_add_u32_e32 v246, v246, v247
	v_lshlrev_b32_e32 v246, 13, v246
	v_bfe_u32 v247, v244, 4, 1
	v_lshlrev_b32_e32 v247, 2, v247
	v_bfe_u32 v248, v245, 5, 2
	v_add_u32_e32 v247, v247, v248
	v_lshl_add_u32 v246, v247, 10, v246
	v_bfe_u32 v247, v245, 3, 2
	v_lshlrev_b32_e32 v247, 4, v247
	v_and_b32_e32 v248, 15, v244
	v_add_u32_e32 v247, v247, v248
	v_lshl_add_u32 v246, v247, 4, v246
	v_add_u32_e32 v246, 0x1080000, v246
	v_mov_b32_e32 v247, 0
	v_readlane_b32 s98, v252, 31
	v_readlane_b32 s99, v252, 32
	s_nop 1
	v_lshl_add_u64 v[246:247], s[98:99], 0, v[246:247]
	global_store_dwordx4 v[246:247], v[50:53], off
	ds_read_b128 v[50:53], v78
	s_waitcnt lgkmcnt(0)
	v_or_b32_e32 v244, v146, v164
	v_lshrrev_b32_e32 v245, 3, v185
	v_add_u32_e32 v244, v244, v245
	v_add_u32_e32 v244, 0x88, v244
	v_and_b32_e32 v245, 7, v185
	v_lshl_add_u32 v245, v245, 3, v114
	v_lshrrev_b32_e32 v246, 5, v244
	v_mul_u32_u24_e32 v246, 0x42, v246
	v_lshrrev_b32_e32 v247, 7, v245
	v_add_u32_e32 v246, v246, v247
	v_lshlrev_b32_e32 v246, 13, v246
	v_bfe_u32 v247, v244, 4, 1
	v_lshlrev_b32_e32 v247, 2, v247
	v_bfe_u32 v248, v245, 5, 2
	v_add_u32_e32 v247, v247, v248
	v_lshl_add_u32 v246, v247, 10, v246
	v_bfe_u32 v247, v245, 3, 2
	v_lshlrev_b32_e32 v247, 4, v247
	v_and_b32_e32 v248, 15, v244
	v_add_u32_e32 v247, v247, v248
	v_lshl_add_u32 v246, v247, 4, v246
	v_add_u32_e32 v246, 0x1080000, v246
	v_mov_b32_e32 v247, 0
	v_readlane_b32 s98, v252, 31
	v_readlane_b32 s99, v252, 32
	s_nop 1
	v_lshl_add_u64 v[246:247], s[98:99], 0, v[246:247]
	global_store_dwordx4 v[246:247], v[50:53], off
	s_branch .LBB0_1034

.LBB0_1157:
	s_ashr_i32 s76, s89, 8
	s_bfe_u32 s84, s89, 0x20006
	s_lshl_b32 s70, s76, 2
	s_or_b32 s70, s70, s84
	s_ashr_i32 s71, s70, 31
	v_readlane_b32 s8, v252, 5
	s_and_b32 s90, s89, 63
	s_lshl_b64 s[72:73], s[70:71], 2
	v_readlane_b32 s10, v252, 7
	v_readlane_b32 s11, v252, 8
	s_add_u32 s72, s10, s72
	s_addc_u32 s73, s11, s73
	global_load_dword v6, v1, s[72:73]
	v_readlane_b32 s9, v252, 6
	v_readlane_b32 s8, v251, 20
	v_readlane_b32 s9, v251, 21
	v_readlane_b32 s12, v252, 9
	v_readlane_b32 s13, v252, 10
	v_readlane_b32 s14, v252, 11
	v_readlane_b32 s15, v252, 12
	s_barrier
	s_and_saveexec_b64 s[78:79], s[8:9]
	s_xor_b64 s[78:79], exec, s[78:79]
	s_lshl_b32 s82, s90, 7
	s_lshl_b32 s72, s84, 8
	s_mov_b32 s73, s83
	s_or_saveexec_b64 s[78:79], s[78:79]
	s_ashr_i32 s77, s76, 31
	v_mov_b64_e32 v[4:5], s[82:83]
	v_mov_b64_e32 v[2:3], s[72:73]
	s_xor_b64 exec, exec, s[78:79]
	s_cbranch_execz .LBB0_1156
	s_lshl_b64 s[80:81], s[76:77], 10
	s_lshl_b32 s82, s84, 8
	s_or_b32 s80, s80, s82
	s_lshl_b32 s72, s90, 7
	s_lshl_b32 s84, s90, 8
	v_readlane_b32 s8, v252, 31
	v_readlane_b32 s9, v252, 32
	s_add_u32 s84, s8, s84
	s_mov_b32 s73, s83
	s_addc_u32 s85, s9, 0
	s_mul_i32 s98, s80, 0x4200
	s_add_u32 s98, s8, s98
	s_addc_u32 s99, s9, 0
	s_mov_b64 s[86:87], 0
	v_mov_b32_e32 v2, v59
	v_mov_b32_e32 v3, v200
.LBB0_1161:
	v_ashrrev_i32_e32 v4, 4, v3
	v_and_b32_e32 v7, 0x78, v2
	v_lshrrev_b32_e32 v8, 5, v4
	v_mul_u32_u24_e32 v8, 0x42, v8
	v_add_u32_e32 v8, s90, v8
	v_lshlrev_b32_e32 v8, 13, v8
	v_bfe_u32 v9, v4, 4, 1
	v_lshlrev_b32_e32 v9, 2, v9
	v_lshrrev_b32_e32 v10, 5, v7
	v_add_u32_e32 v9, v9, v10
	v_lshl_add_u32 v8, v9, 10, v8
	v_bfe_u32 v9, v7, 3, 2
	v_lshlrev_b32_e32 v9, 4, v9
	v_and_b32_e32 v10, 15, v4
	v_add_u32_e32 v9, v9, v10
	v_lshl_add_u32 v8, v9, 4, v8
	v_mov_b32_e32 v9, 0
	v_lshl_add_u64 v[8:9], s[98:99], 0, v[8:9]
	global_load_dwordx4 v[8:11], v[8:9], off
	v_lshlrev_b32_e32 v0, 1, v4
	v_mul_u32_u24_e32 v4, 0x210, v7
	v_add3_u32 v0, 16, v0, v4
	s_movk_i32 s91, 0xdff
	v_cmp_lt_i32_e32 vcc, s91, v3
	v_add_u32_e32 v2, 0x1000, v2
	s_or_b64 s[86:87], vcc, s[86:87]
	s_waitcnt vmcnt(0)
	ds_write_b16 v0, v8
	ds_write_b16_d16_hi v0, v8 offset:528
	ds_write_b16 v0, v9 offset:1056
	ds_write_b16_d16_hi v0, v9 offset:1584
	ds_write_b16 v0, v10 offset:2112
	ds_write_b16_d16_hi v0, v10 offset:2640
	ds_write_b16 v0, v11 offset:3168
	ds_write_b16_d16_hi v0, v11 offset:3696
	v_add_u32_e32 v0, 0x200, v3
	v_mov_b32_e32 v3, v0
	s_andn2_b64 exec, exec, s[86:87]
	s_cbranch_execnz .LBB0_1161
	s_or_b64 exec, exec, s[86:87]
	v_mov_b64_e32 v[4:5], s[72:73]
	v_mov_b64_e32 v[2:3], s[82:83]
	s_branch .LBB0_1156

.LBB0_1218:
	s_lshl_b32 s6, s18, 5
	s_and_b32 s16, s6, 0xe0
	s_ashr_i32 s6, s18, 3
	s_add_i32 s16, s16, s6
	s_ashr_i32 s10, s16, 7
	s_and_b32 s14, s6, 31
	s_bfe_u32 s15, s16, 0x20005
	s_lshl_b32 s6, s10, 2
	s_or_b32 s8, s6, s15
	s_ashr_i32 s9, s8, 31
	s_lshl_b64 s[6:7], s[8:9], 2
	s_add_u32 s6, s54, s6
	s_addc_u32 s7, s55, s7
	global_load_dword v40, v1, s[6:7]
	s_lshl_b32 s6, s15, 9
	s_lshl_b32 s7, s14, 4
	s_ashr_i32 s11, s10, 31
	s_or_b32 s17, s6, s7
	s_lshl_b32 s19, s15, 8
	s_lshl_b64 s[6:7], s[10:11], 10
	s_or_b32 s6, s6, s19
	v_lshl_add_u64 v[2:3], s[6:7], 0, v[126:127]
	v_mad_u64_u32 v[142:143], s[6:7], v2, s88, v[128:129]
	v_mov_b32_e32 v0, v143
	v_mad_u64_u32 v[2:3], s[6:7], v3, s88, v[0:1]
	s_cmpk_gt_u32 s16, 0x7f
	s_cselect_b64 s[6:7], -1, 0
	s_and_b64 s[12:13], s[6:7], exec
	s_movk_i32 s12, 0x2080
	s_cselect_b32 s12, s12, 0x2000
	v_mov_b32_e32 v143, v2
	v_mbcnt_lo_u32_b32 v100, -1, 0
	v_mbcnt_hi_u32_b32 v100, -1, v100
	v_lshrrev_b32_e32 v102, 4, v100
	v_mul_u32_u24_e32 v104, 0x4100, v102
	v_sub_u32_e32 v104, 0, v104
	v_ashrrev_i32_e32 v105, 31, v104
	v_lshl_add_u64 v[142:143], v[142:143], 0, v[104:105]
	s_lshl_b32 s82, s12, 6
	v_lshl_add_u64 v[2:3], v[142:143], 0, s[82:83]
	global_load_dwordx4 v[4:7], v[2:3], off
	global_load_dwordx4 v[8:11], v[2:3], off offset:1024
	global_load_dwordx4 v[12:15], v[2:3], off offset:2048
	global_load_dwordx4 v[16:19], v[2:3], off offset:3072
	v_add_co_u32_e32 v20, vcc, 0x1000, v2
	s_nop 1
	v_addc_co_u32_e32 v21, vcc, 0, v3, vcc
	global_load_dwordx4 v[24:27], v[20:21], off
	global_load_dwordx4 v[28:31], v[20:21], off offset:1024
	global_load_dwordx4 v[32:35], v[20:21], off offset:2048
	global_load_dwordx4 v[36:39], v[20:21], off offset:3072
	s_lshl_b32 s82, s12, 1
	v_or_b32_e32 v0, s17, v123
	v_mul_u32_u24_e32 v0, 0x2100, v0
	v_lshlrev_b32_e32 v0, 1, v0
	v_mov_b32_e32 v2, v1
	v_mov_b32_e32 v3, v1
	v_lshl_add_u64 v[144:145], v[132:133], 0, v[0:1]
	v_mov_b32_e32 v0, v1
	v_mov_b64_e32 v[22:23], v[2:3]
	v_mov_b64_e32 v[20:21], v[0:1]
	s_and_saveexec_b64 s[12:13], s[0:1]
	s_cbranch_execz .LBB0_1220
	v_lshl_add_u64 v[20:21], v[144:145], 0, s[82:83]
	global_load_dwordx4 v[20:23], v[20:21], off

.LBB0_1221:
	s_add_i32 s20, s20, -1
	s_cmp_eq_u32 s21, 64
	s_mov_b32 s9, s21
	s_cbranch_scc1 .LBB0_1217

.Lscan_kw:
	v_mov_b32_e32 v147, v146
	v_pk_mul_f32 v[94:95], v[146:147], v[94:95]
	v_pk_mul_f32 v[92:93], v[156:157], v[92:93]
	v_pk_mul_f32 v[98:99], v[146:147], v[98:99]
	v_pk_mul_f32 v[96:97], v[156:157], v[96:97]
	s_nop 1
	v_mfma_f32_16x16x32_bf16 v[92:95], v[4:7], v[112:115], v[92:95]
	v_mfma_f32_16x16x32_bf16 v[96:99], v[24:27], v[112:115], v[96:99]
	v_mfma_f32_16x16x32_bf16 v[92:95], v[8:11], v[108:111], v[92:95]
	v_mfma_f32_16x16x32_bf16 v[96:99], v[28:31], v[108:111], v[96:99]
	v_mfma_f32_16x16x32_bf16 v[92:95], v[12:15], v[104:107], v[92:95]
	v_mfma_f32_16x16x32_bf16 v[96:99], v[32:35], v[104:107], v[96:99]
	v_mfma_f32_16x16x32_bf16 v[92:95], v[16:19], v[100:103], v[92:95]
	v_mfma_f32_16x16x32_bf16 v[96:99], v[36:39], v[100:103], v[96:99]
	s_cbranch_vccnz .LBB0_1221
	s_lshl_b32 s16, s10, 6
	s_mov_b32 s17, 0
	v_lshl_add_u64 v[2:3], v[142:143], 0, s[16:17]
	global_load_dwordx4 v[4:7], v[2:3], off
	global_load_dwordx4 v[8:11], v[2:3], off offset:1024
	global_load_dwordx4 v[12:15], v[2:3], off offset:2048
	global_load_dwordx4 v[16:19], v[2:3], off offset:3072
	s_movk_i32 s16, 0x1000
	v_lshl_add_u64 v[2:3], v[2:3], 0, s[16:17]
	global_load_dwordx4 v[24:27], v[2:3], off
	global_load_dwordx4 v[28:31], v[2:3], off offset:1024
	global_load_dwordx4 v[32:35], v[2:3], off offset:2048
	global_load_dwordx4 v[36:39], v[2:3], off offset:3072
	s_branch .LBB0_1221
